# lin_C2 (phases 6,15): de-serialised C_prev and Q staging loads (all loads in flight, counted vmcnt waits)
# speedup vs baseline: 1.0088x; 1.0088x over previous
.LBB0_73:
	s_ashr_i32 s13, s12, 31
	s_lshl_b64 s[14:15], s[12:13], 16
	v_lshl_add_u64 v[12:13], v[36:37], 0, s[14:15]
	v_lshl_add_u64 v[8:9], v[46:47], 2, v[12:13]
	v_lshl_add_u64 v[56:57], v[48:49], 2, v[12:13]
	v_lshl_add_u64 v[58:59], v[50:51], 2, v[12:13]
	v_lshl_add_u64 v[60:61], v[52:53], 2, v[12:13]
	s_and_saveexec_b64 s[14:15], s[4:5]
	s_cbranch_execz .Llc2f_ns_issued
	v_lshl_add_u32 v62, s12, 7, v88
	v_ashrrev_i32_e32 v63, 31, v62
	v_lshl_add_u64 v[62:63], v[62:63], 2, s[8:9]
	global_load_dword v2, v[62:63], off
.Llc2f_ns_issued:
	s_or_b64 exec, exec, s[14:15]
	global_load_dwordx4 v[4:7], v[8:9], off offset:16
	global_load_dwordx4 v[14:17], v[8:9], off
	global_load_dwordx4 v[18:21], v[56:57], off offset:16
	global_load_dwordx4 v[22:25], v[56:57], off
	global_load_dwordx4 v[26:29], v[58:59], off offset:16
	global_load_dwordx4 v[30:33], v[58:59], off
	global_load_dwordx4 v[64:67], v[60:61], off offset:16
	global_load_dwordx4 v[68:71], v[60:61], off
	s_barrier
	s_waitcnt vmcnt(6)
	v_cvt_pk_bf16_f32 v8, v14, v15
	v_cvt_pk_bf16_f32 v9, v16, v17
	v_cvt_pk_bf16_f32 v10, v4, v5
	v_cvt_pk_bf16_f32 v11, v6, v7
	ds_write_b128 v96, v[8:11]
	s_waitcnt vmcnt(4)
	v_cvt_pk_bf16_f32 v72, v22, v23
	v_cvt_pk_bf16_f32 v73, v24, v25
	v_cvt_pk_bf16_f32 v74, v18, v19
	v_cvt_pk_bf16_f32 v75, v20, v21
	ds_write_b128 v96, v[72:75] offset:8704
	s_waitcnt vmcnt(2)
	v_cvt_pk_bf16_f32 v76, v30, v31
	v_cvt_pk_bf16_f32 v77, v32, v33
	v_cvt_pk_bf16_f32 v78, v26, v27
	v_cvt_pk_bf16_f32 v79, v28, v29
	ds_write_b128 v96, v[76:79] offset:17408
	s_waitcnt vmcnt(0)
	v_cvt_pk_bf16_f32 v80, v68, v69
	v_cvt_pk_bf16_f32 v81, v70, v71
	v_cvt_pk_bf16_f32 v82, v64, v65
	v_cvt_pk_bf16_f32 v83, v66, v67
	ds_write_b128 v96, v[80:83] offset:26112
	s_and_saveexec_b64 s[14:15], s[4:5]
	s_cbranch_execz .LBB0_75
	ds_write_b32 v89, v2

.LBB0_76:
	v_lshl_add_u64 v[4:5], v[56:57], 0, s[16:17]
	v_mad_u64_u32 v[8:9], s[18:19], v4, s72, v[58:59]
	v_mov_b32_e32 v2, v9
	v_mad_u64_u32 v[10:11], s[18:19], v5, s72, v[2:3]
	v_mov_b32_e32 v9, v10
	v_add_co_u32_e32 v114, vcc, s20, v8
	s_nop 1
	v_addc_co_u32_e32 v115, vcc, 0, v10, vcc
	v_add_co_u32_e32 v116, vcc, s24, v8
	s_nop 1
	v_addc_co_u32_e32 v117, vcc, 0, v10, vcc
	v_add_co_u32_e32 v118, vcc, s25, v8
	s_nop 1
	v_addc_co_u32_e32 v119, vcc, 0, v10, vcc
	global_load_dwordx4 v[120:123], v[8:9], off
	global_load_dwordx4 v[124:127], v[114:115], off
	global_load_dwordx4 v[128:131], v[116:117], off
	global_load_dwordx4 v[132:135], v[118:119], off
	v_lshl_add_u64 v[98:99], v[60:61], 0, s[16:17]
	v_mad_u64_u32 v[70:71], s[16:17], v98, s72, v[66:67]
	v_mov_b32_e32 v2, v71
	v_lshlrev_b64 v[84:85], 11, v[98:99]
	v_add_u32_e32 v110, v43, v42
	v_mad_u64_u32 v[6:7], s[16:17], v99, s72, v[2:3]
	v_lshlrev_b64 v[98:99], 4, v[98:99]
	v_lshl_or_b32 v98, s13, 2, v98
	v_lshl_add_u64 v[4:5], v[62:63], 0, v[84:85]
	v_mov_b32_e32 v71, v6
	v_lshl_add_u64 v[100:101], s[6:7], 0, v[98:99]
	v_lshl_add_u64 v[98:99], s[0:1], 0, v[98:99]
	global_load_dwordx4 v[32:35], v[4:5], off
	global_load_dwordx2 v[86:87], v[70:71], off offset:3072
	global_load_dwordx4 v[28:31], v[4:5], off offset:64
	global_load_dwordx2 v[82:83], v[70:71], off offset:3104
	global_load_dwordx4 v[24:27], v[4:5], off offset:128
	global_load_dwordx2 v[80:81], v[70:71], off offset:3136
	global_load_dwordx4 v[20:23], v[4:5], off offset:192
	global_load_dwordx2 v[78:79], v[70:71], off offset:3168
	global_load_dwordx4 v[16:19], v[4:5], off offset:256
	global_load_dwordx2 v[76:77], v[70:71], off offset:3200
	global_load_dwordx4 v[12:15], v[4:5], off offset:320
	global_load_dwordx2 v[74:75], v[70:71], off offset:3232
	global_load_dwordx4 v[8:11], v[4:5], off offset:384
	global_load_dwordx2 v[72:73], v[70:71], off offset:3264
	s_nop 0
	global_load_dwordx4 v[4:7], v[4:5], off offset:448
	s_nop 0
	global_load_dwordx2 v[70:71], v[70:71], off offset:3296
	s_nop 0
	global_load_dword v2, v[100:101], off
	global_load_dword v97, v[98:99], off
	s_waitcnt lgkmcnt(0)
	s_barrier
	s_waitcnt vmcnt(21)
	ds_write_b128 v96, v[120:123] offset:34816
	s_waitcnt vmcnt(20)
	ds_write_b128 v96, v[124:127] offset:43520
	s_waitcnt vmcnt(19)
	ds_write_b128 v96, v[128:131] offset:52224
	s_waitcnt vmcnt(18)
	ds_write_b128 v96, v[132:135] offset:60928
	s_waitcnt lgkmcnt(0)
	s_barrier
	ds_read_b128 v[98:101], v110 offset:34816
	ds_read_b128 v[102:105], v110 offset:34880
	ds_read_b128 v[106:109], v110 offset:34944
	ds_read_b128 v[110:113], v110 offset:35008
	ds_read_b128 v[114:117], v93
	ds_read_b128 v[118:121], v93 offset:64
	ds_read_b128 v[122:125], v93 offset:4416
	s_waitcnt lgkmcnt(2)
	v_mfma_f32_16x16x32_bf16 v[114:117], v[114:117], v[98:101], 0
	ds_read_b128 v[126:129], v93 offset:8768
	ds_read_b128 v[130:133], v93 offset:13120
	ds_read_b128 v[134:137], v93 offset:17472
	s_waitcnt lgkmcnt(4)
	v_mfma_f32_16x16x32_bf16 v[114:117], v[118:121], v[102:105], v[114:117]
	ds_read_b128 v[118:121], v93 offset:128
	ds_read_b128 v[138:141], v93 offset:21824
	ds_read_b128 v[142:145], v93 offset:26176
	s_waitcnt lgkmcnt(2)
	v_mfma_f32_16x16x32_bf16 v[114:117], v[118:121], v[106:109], v[114:117]
	ds_read_b128 v[118:121], v93 offset:192
	s_waitcnt vmcnt(1)
	v_mul_f32_e32 v2, 0x3db504f3, v2
	s_waitcnt lgkmcnt(0)
	v_mfma_f32_16x16x32_bf16 v[114:117], v[118:121], v[110:113], v[114:117]
	ds_read_b128 v[118:121], v93 offset:4352
	s_waitcnt lgkmcnt(0)
	v_mfma_f32_16x16x32_bf16 v[118:121], v[118:121], v[98:101], 0
	s_nop 4
	v_fma_f32 v32, v2, v114, v32
	v_fma_f32 v33, v2, v115, v33
	v_pk_fma_f32 v[34:35], v[2:3], v[116:117], v[34:35] op_sel_hi:[0,1,1]
	v_mfma_f32_16x16x32_bf16 v[118:121], v[122:125], v[102:105], v[118:121]
	ds_read_b128 v[122:125], v93 offset:4480
	s_waitcnt lgkmcnt(0)
	v_mfma_f32_16x16x32_bf16 v[118:121], v[122:125], v[106:109], v[118:121]
	ds_read_b128 v[122:125], v93 offset:4544
	s_waitcnt lgkmcnt(0)
	v_mfma_f32_16x16x32_bf16 v[118:121], v[122:125], v[110:113], v[118:121]
	ds_read_b128 v[122:125], v93 offset:8704
	s_waitcnt lgkmcnt(0)
	v_mfma_f32_16x16x32_bf16 v[122:125], v[122:125], v[98:101], 0
	v_mfma_f32_16x16x32_bf16 v[122:125], v[126:129], v[102:105], v[122:125]
	ds_read_b128 v[126:129], v93 offset:8832
	s_waitcnt lgkmcnt(0)
	v_mfma_f32_16x16x32_bf16 v[122:125], v[126:129], v[106:109], v[122:125]
	ds_read_b128 v[126:129], v93 offset:8896
	s_waitcnt lgkmcnt(0)
	v_mfma_f32_16x16x32_bf16 v[122:125], v[126:129], v[110:113], v[122:125]
	ds_read_b128 v[126:129], v93 offset:13056
	s_nop 6
	v_pk_fma_f32 v[24:25], v[2:3], v[122:123], v[24:25] op_sel_hi:[0,1,1]
	s_waitcnt lgkmcnt(0)
	v_mfma_f32_16x16x32_bf16 v[126:129], v[126:129], v[98:101], 0
	v_mfma_f32_16x16x32_bf16 v[126:129], v[130:133], v[102:105], v[126:129]
	ds_read_b128 v[130:133], v93 offset:13184
	s_waitcnt lgkmcnt(0)
	v_mfma_f32_16x16x32_bf16 v[126:129], v[130:133], v[106:109], v[126:129]
	ds_read_b128 v[130:133], v93 offset:13248
	s_waitcnt lgkmcnt(0)
	v_mfma_f32_16x16x32_bf16 v[126:129], v[130:133], v[110:113], v[126:129]
	ds_read_b128 v[130:133], v93 offset:17408
	s_waitcnt lgkmcnt(0)
	v_mfma_f32_16x16x32_bf16 v[130:133], v[130:133], v[98:101], 0
	v_mfma_f32_16x16x32_bf16 v[130:133], v[134:137], v[102:105], v[130:133]
	ds_read_b128 v[134:137], v93 offset:17536
	s_waitcnt lgkmcnt(0)
	v_mfma_f32_16x16x32_bf16 v[130:133], v[134:137], v[106:109], v[130:133]
	ds_read_b128 v[134:137], v93 offset:17600
	s_waitcnt lgkmcnt(0)
	v_mfma_f32_16x16x32_bf16 v[130:133], v[134:137], v[110:113], v[130:133]
	ds_read_b128 v[134:137], v93 offset:21760
	s_waitcnt lgkmcnt(0)
	v_mfma_f32_16x16x32_bf16 v[134:137], v[134:137], v[98:101], 0
	v_mfma_f32_16x16x32_bf16 v[134:137], v[138:141], v[102:105], v[134:137]
	ds_read_b128 v[138:141], v93 offset:21888
	s_waitcnt lgkmcnt(0)
	v_mfma_f32_16x16x32_bf16 v[134:137], v[138:141], v[106:109], v[134:137]
	ds_read_b128 v[138:141], v93 offset:21952
	s_waitcnt lgkmcnt(0)
	v_mfma_f32_16x16x32_bf16 v[134:137], v[138:141], v[110:113], v[134:137]
	ds_read_b128 v[138:141], v93 offset:26112
	s_nop 6
	v_pk_fma_f32 v[12:13], v[2:3], v[134:135], v[12:13] op_sel_hi:[0,1,1]
	s_waitcnt lgkmcnt(0)
	v_mfma_f32_16x16x32_bf16 v[138:141], v[138:141], v[98:101], 0
	v_mfma_f32_16x16x32_bf16 v[138:141], v[142:145], v[102:105], v[138:141]
	ds_read_b128 v[142:145], v93 offset:26240
	s_waitcnt lgkmcnt(0)
	v_mfma_f32_16x16x32_bf16 v[138:141], v[142:145], v[106:109], v[138:141]
	ds_read_b128 v[142:145], v93 offset:26304
	s_waitcnt lgkmcnt(0)
	v_mfma_f32_16x16x32_bf16 v[138:141], v[142:145], v[110:113], v[138:141]
	ds_read_b128 v[142:145], v93 offset:30464
	s_waitcnt lgkmcnt(0)
	v_mfma_f32_16x16x32_bf16 v[98:101], v[142:145], v[98:101], 0
	ds_read_b128 v[142:145], v93 offset:30528
	s_waitcnt lgkmcnt(0)
	v_mfma_f32_16x16x32_bf16 v[98:101], v[142:145], v[102:105], v[98:101]
	ds_read_b128 v[102:105], v93 offset:30592
	s_waitcnt lgkmcnt(0)
	v_mfma_f32_16x16x32_bf16 v[98:101], v[102:105], v[106:109], v[98:101]
	ds_read_b128 v[102:105], v93 offset:30656
	s_waitcnt lgkmcnt(0)
	v_mfma_f32_16x16x32_bf16 v[98:101], v[102:105], v[110:113], v[98:101]
	ds_read_b128 v[102:105], v94 offset:34816
	ds_read_b128 v[106:109], v94 offset:34832
	ds_read_b128 v[110:113], v94 offset:34848
	ds_read_b128 v[142:145], v94 offset:34864
	ds_read_b128 v[146:149], v95
	ds_read_b128 v[150:153], v95 offset:16
	ds_read_b128 v[154:157], v95 offset:32
	ds_read_b128 v[158:161], v95 offset:48
	s_waitcnt lgkmcnt(7)
	v_and_b32_e32 v166, 0xffff0000, v102
	s_waitcnt lgkmcnt(6)
	v_and_b32_e32 v167, 0xffff0000, v106
	v_lshlrev_b32_e32 v163, 16, v106
	s_waitcnt lgkmcnt(1)
	v_mov_b32_e32 v165, v154
	v_mov_b32_e32 v154, v147
	v_lshlrev_b32_e32 v162, 16, v102
	v_mov_b32_e32 v164, v146
	v_pk_mul_f32 v[146:147], v[154:155], v[166:167]
	v_lshlrev_b32_e32 v155, 16, v107
	v_pk_fma_f32 v[146:147], v[164:165], v[162:163], v[146:147]
	v_lshlrev_b32_e32 v154, 16, v103
	v_mov_b32_e32 v162, v148
	v_mov_b32_e32 v163, v156
	v_pk_fma_f32 v[146:147], v[162:163], v[154:155], v[146:147]
	v_and_b32_e32 v107, 0xffff0000, v107
	v_and_b32_e32 v106, 0xffff0000, v103
	v_mov_b32_e32 v156, v149
	v_pk_fma_f32 v[102:103], v[156:157], v[106:107], v[146:147]
	v_lshlrev_b32_e32 v107, 16, v108
	v_lshlrev_b32_e32 v106, 16, v104
	v_mov_b32_e32 v146, v150
	s_waitcnt lgkmcnt(0)
	v_mov_b32_e32 v147, v158
	v_pk_fma_f32 v[102:103], v[146:147], v[106:107], v[102:103]
	v_and_b32_e32 v107, 0xffff0000, v108
	v_and_b32_e32 v106, 0xffff0000, v104
	v_mov_b32_e32 v158, v151
	v_pk_fma_f32 v[102:103], v[158:159], v[106:107], v[102:103]
	v_lshlrev_b32_e32 v107, 16, v109
	v_lshlrev_b32_e32 v106, 16, v105
	v_mov_b32_e32 v146, v152
	v_mov_b32_e32 v147, v160
	v_pk_fma_f32 v[102:103], v[146:147], v[106:107], v[102:103]
	v_and_b32_e32 v107, 0xffff0000, v109
	v_and_b32_e32 v106, 0xffff0000, v105
	v_mov_b32_e32 v160, v153
	v_pk_fma_f32 v[102:103], v[160:161], v[106:107], v[102:103]
	v_and_b32_e32 v159, 0xffff0000, v142
	v_add_f32_e32 v102, 0, v102
	v_add_f32_e32 v160, v102, v103
	ds_read_b128 v[102:105], v95 offset:80
	ds_read_b128 v[106:109], v95 offset:112
	ds_read_b128 v[146:149], v95 offset:64
	ds_read_b128 v[150:153], v95 offset:96
	v_and_b32_e32 v158, 0xffff0000, v110
	v_lshlrev_b32_e32 v155, 16, v142
	v_lshlrev_b32_e32 v154, 16, v110
	s_waitcnt lgkmcnt(1)
	v_mov_b32_e32 v156, v146
	s_waitcnt lgkmcnt(0)
	v_mov_b32_e32 v157, v150
	v_mov_b32_e32 v150, v147
	v_pk_mul_f32 v[146:147], v[150:151], v[158:159]
	v_lshlrev_b32_e32 v151, 16, v143
	v_pk_fma_f32 v[146:147], v[156:157], v[154:155], v[146:147]
	v_lshlrev_b32_e32 v150, 16, v111
	v_mov_b32_e32 v154, v148
	v_mov_b32_e32 v155, v152
	v_pk_fma_f32 v[146:147], v[154:155], v[150:151], v[146:147]
	v_and_b32_e32 v143, 0xffff0000, v143
	v_and_b32_e32 v142, 0xffff0000, v111
	v_mov_b32_e32 v152, v149
	v_pk_fma_f32 v[110:111], v[152:153], v[142:143], v[146:147]
	v_lshlrev_b32_e32 v143, 16, v144
	v_lshlrev_b32_e32 v142, 16, v112
	v_mov_b32_e32 v146, v102
	v_mov_b32_e32 v147, v106
	v_pk_fma_f32 v[110:111], v[146:147], v[142:143], v[110:111]
	v_and_b32_e32 v143, 0xffff0000, v144
	v_and_b32_e32 v142, 0xffff0000, v112
	v_mov_b32_e32 v106, v103
	v_pk_fma_f32 v[102:103], v[106:107], v[142:143], v[110:111]
	v_lshlrev_b32_e32 v107, 16, v145
	v_lshlrev_b32_e32 v106, 16, v113
	v_mov_b32_e32 v110, v104
	v_mov_b32_e32 v111, v108
	v_pk_fma_f32 v[102:103], v[110:111], v[106:107], v[102:103]
	v_and_b32_e32 v107, 0xffff0000, v145
	v_and_b32_e32 v106, 0xffff0000, v113
	v_mov_b32_e32 v108, v105
	v_pk_fma_f32 v[102:103], v[108:109], v[106:107], v[102:103]
	v_pk_fma_f32 v[112:113], v[2:3], v[130:131], v[16:17] op_sel_hi:[0,1,1]
	v_add_f32_e32 v102, v160, v102
	v_add_f32_e32 v102, v102, v103
	ds_bpermute_b32 v103, v91, v102
	v_pk_fma_f32 v[16:17], v[2:3], v[132:133], v[18:19] op_sel_hi:[0,1,1]
	v_pk_fma_f32 v[98:99], v[2:3], v[98:99], v[4:5] op_sel_hi:[0,1,1]
	v_pk_fma_f32 v[4:5], v[2:3], v[100:101], v[6:7] op_sel_hi:[0,1,1]
	s_waitcnt lgkmcnt(0)
	v_add_f32_e32 v102, v102, v103
	ds_bpermute_b32 v103, v92, v102
	s_waitcnt lgkmcnt(0)
	v_add_f32_e32 v102, v102, v103
	s_waitcnt vmcnt(0)
	v_fmac_f32_e32 v97, v2, v102
	v_max_f32_e64 v97, |v97|, 1.0
	v_div_scale_f32 v102, s[16:17], v97, v97, 1.0
	v_rcp_f32_e32 v103, v102
	s_mov_b64 s[16:17], 0x80
	v_fma_f32 v104, -v102, v103, 1.0
	v_fmac_f32_e32 v103, v104, v103
	v_div_scale_f32 v104, vcc, 1.0, v97, 1.0
	v_mul_f32_e32 v105, v104, v103
	v_fma_f32 v106, -v102, v105, v104
	v_fmac_f32_e32 v105, v106, v103
	v_fma_f32 v102, -v102, v105, v104
	v_div_fmas_f32 v102, v102, v103, v105
	v_div_fixup_f32 v102, v102, v97, 1.0
	v_pk_mul_f32 v[106:107], v[32:33], v[102:103] op_sel_hi:[1,0]
	v_pk_fma_f32 v[32:33], v[2:3], v[118:119], v[28:29] op_sel_hi:[0,1,1]
	v_pk_fma_f32 v[28:29], v[2:3], v[120:121], v[30:31] op_sel_hi:[0,1,1]
	v_pk_mul_f32 v[30:31], v[32:33], v[102:103] op_sel_hi:[1,0]
	v_pk_mul_f32 v[104:105], v[34:35], v[102:103] op_sel_hi:[1,0]
	v_pk_mul_f32 v[28:29], v[28:29], v[102:103] op_sel_hi:[1,0]
	v_mov_b32_e32 v34, v107
	v_mov_b32_e32 v35, v31
	v_mov_b32_e32 v32, v106
	v_mov_b32_e32 v33, v30
	v_pk_mul_f32 v[34:35], v[34:35], v[34:35]
	v_mov_b32_e32 v108, v105
	v_mov_b32_e32 v109, v29
	v_pk_fma_f32 v[32:33], v[32:33], v[32:33], v[34:35]
	v_mov_b32_e32 v34, v104
	v_mov_b32_e32 v35, v28
	v_pk_mul_f32 v[108:109], v[108:109], v[108:109]
	v_pk_mul_f32 v[16:17], v[16:17], v[102:103] op_sel_hi:[1,0]
	v_pk_fma_f32 v[34:35], v[34:35], v[34:35], v[108:109]
	v_pk_mul_f32 v[18:19], v[112:113], v[102:103] op_sel_hi:[1,0]
	v_pk_add_f32 v[32:33], v[32:33], v[34:35]
	v_pk_fma_f32 v[34:35], v[2:3], v[124:125], v[26:27] op_sel_hi:[0,1,1]
	v_pk_mul_f32 v[26:27], v[24:25], v[102:103] op_sel_hi:[1,0]
	v_pk_mul_f32 v[24:25], v[34:35], v[102:103] op_sel_hi:[1,0]
	v_pk_mul_f32 v[108:109], v[26:27], v[26:27]
	v_pk_mul_f32 v[34:35], v[24:25], v[24:25]
	v_pk_add_f32 v[32:33], v[32:33], v[32:33] op_sel_hi:[0,1]
	v_pk_mov_b32 v[110:111], v[108:109], v[34:35] op_sel:[1,0]
	v_mov_b32_e32 v109, v35
	v_pk_add_f32 v[34:35], v[110:111], v[108:109]
	v_pk_fma_f32 v[108:109], v[2:3], v[126:127], v[20:21] op_sel_hi:[0,1,1]
	v_pk_fma_f32 v[20:21], v[2:3], v[128:129], v[22:23] op_sel_hi:[0,1,1]
	v_pk_mul_f32 v[22:23], v[108:109], v[102:103] op_sel_hi:[1,0]
	v_pk_mul_f32 v[20:21], v[20:21], v[102:103] op_sel_hi:[1,0]
	v_mul_f32_e32 v32, v22, v22
	v_pk_add_f32 v[34:35], v[34:35], v[34:35] op_sel_hi:[0,1]
	v_pk_fma_f32 v[108:109], v[22:23], v[22:23], v[32:33] op_sel_hi:[1,1,0]
	v_mul_f32_e32 v32, v20, v20
	v_pk_fma_f32 v[110:111], v[20:21], v[20:21], v[32:33] op_sel_hi:[1,1,0]
	v_mul_f32_e32 v34, v16, v16
	v_mul_f32_e32 v32, v17, v17
	v_mul_f32_e32 v108, v18, v18
	v_mul_f32_e32 v110, v19, v19
	v_pk_add_f32 v[32:33], v[34:35], v[32:33]
	v_pk_fma_f32 v[34:35], v[2:3], v[136:137], v[14:15] op_sel_hi:[0,1,1]
	v_pk_add_f32 v[108:109], v[108:109], v[110:111]
	v_pk_mul_f32 v[14:15], v[12:13], v[102:103] op_sel_hi:[1,0]
	v_pk_mul_f32 v[12:13], v[34:35], v[102:103] op_sel_hi:[1,0]
	v_pk_add_f32 v[32:33], v[108:109], v[32:33]
	v_pk_mul_f32 v[34:35], v[12:13], v[12:13]
	v_pk_mul_f32 v[108:109], v[14:15], v[14:15]
	v_pk_add_f32 v[32:33], v[32:33], v[32:33] op_sel_hi:[0,1]
	v_pk_mov_b32 v[110:111], v[108:109], v[34:35] op_sel:[1,0]
	v_mov_b32_e32 v109, v35
	v_pk_add_f32 v[34:35], v[110:111], v[108:109]
	v_pk_fma_f32 v[108:109], v[2:3], v[138:139], v[8:9] op_sel_hi:[0,1,1]
	v_pk_fma_f32 v[8:9], v[2:3], v[140:141], v[10:11] op_sel_hi:[0,1,1]
	v_pk_mul_f32 v[10:11], v[108:109], v[102:103] op_sel_hi:[1,0]
	v_pk_mul_f32 v[8:9], v[8:9], v[102:103] op_sel_hi:[1,0]
	v_mul_f32_e32 v32, v10, v10
	v_pk_fma_f32 v[108:109], v[10:11], v[10:11], v[32:33] op_sel_hi:[1,1,0]
	v_mul_f32_e32 v32, v8, v8
	v_pk_add_f32 v[34:35], v[34:35], v[34:35] op_sel_hi:[0,1]
	v_pk_fma_f32 v[110:111], v[8:9], v[8:9], v[32:33] op_sel_hi:[1,1,0]
	v_pk_mul_f32 v[4:5], v[4:5], v[102:103] op_sel_hi:[1,0]
	v_pk_mul_f32 v[6:7], v[98:99], v[102:103] op_sel_hi:[1,0]
	v_mul_f32_e32 v34, v4, v4
	v_mul_f32_e32 v108, v6, v6
	v_mul_f32_e32 v110, v7, v7
	v_mul_f32_e32 v32, v5, v5
	v_pk_add_f32 v[98:99], v[108:109], v[110:111]
	v_pk_add_f32 v[32:33], v[34:35], v[32:33]
	v_lshlrev_b32_e32 v97, 16, v86
	v_pk_add_f32 v[32:33], v[98:99], v[32:33]
	v_and_b32_e32 v86, 0xffff0000, v86
	v_add_f32_e32 v2, v32, v33
	ds_bpermute_b32 v32, v91, v2
	v_mul_f32_e32 v86, 0xbfb8aa3b, v86
	v_exp_f32_e32 v86, v86
	v_mul_f32_e32 v97, 0xbfb8aa3b, v97
	v_exp_f32_e32 v97, v97
	s_waitcnt lgkmcnt(0)
	v_add_f32_e32 v2, v2, v32
	ds_bpermute_b32 v32, v92, v2
	v_add_f32_e32 v86, 1.0, v86
	v_rcp_f32_e32 v99, v86
	v_lshlrev_b32_e32 v86, 16, v87
	v_and_b32_e32 v87, 0xffff0000, v87
	s_waitcnt lgkmcnt(0)
	v_add_f32_e32 v2, v2, v32
	v_fmamk_f32 v2, v2, 0x3c000000, v172
	v_cmp_gt_f32_e32 vcc, s33, v2
	v_mul_f32_e32 v32, 0x4b800000, v2
	v_mul_f32_e32 v86, 0xbfb8aa3b, v86
	v_cndmask_b32_e32 v2, v2, v32, vcc
	v_rsq_f32_e32 v2, v2
	v_mul_f32_e32 v87, 0xbfb8aa3b, v87
	v_exp_f32_e32 v86, v86
	v_exp_f32_e32 v87, v87
	v_mul_f32_e32 v32, 0x45800000, v2
	v_cndmask_b32_e32 v2, v2, v32, vcc
	global_load_dwordx4 v[32:35], v[64:65], off
	v_add_f32_e32 v97, 1.0, v97
	v_rcp_f32_e32 v98, v97
	v_add_f32_e32 v86, 1.0, v86
	v_add_f32_e32 v87, 1.0, v87
	v_pk_mul_f32 v[100:101], v[106:107], v[2:3] op_sel_hi:[1,0]
	v_rcp_f32_e32 v86, v86
	v_rcp_f32_e32 v87, v87
	v_pk_mul_f32 v[30:31], v[30:31], v[2:3] op_sel_hi:[1,0]
	v_pk_mul_f32 v[28:29], v[28:29], v[2:3] op_sel_hi:[1,0]
	v_pk_mul_f32 v[26:27], v[26:27], v[2:3] op_sel_hi:[1,0]
	v_pk_mul_f32 v[24:25], v[24:25], v[2:3] op_sel_hi:[1,0]
	v_pk_mul_f32 v[22:23], v[22:23], v[2:3] op_sel_hi:[1,0]
	v_pk_mul_f32 v[20:21], v[20:21], v[2:3] op_sel_hi:[1,0]
	v_pk_mul_f32 v[18:19], v[18:19], v[2:3] op_sel_hi:[1,0]
	v_pk_mul_f32 v[16:17], v[16:17], v[2:3] op_sel_hi:[1,0]
	v_pk_mul_f32 v[14:15], v[14:15], v[2:3] op_sel_hi:[1,0]
	v_pk_mul_f32 v[12:13], v[12:13], v[2:3] op_sel_hi:[1,0]
	v_pk_mul_f32 v[10:11], v[10:11], v[2:3] op_sel_hi:[1,0]
	v_pk_mul_f32 v[8:9], v[8:9], v[2:3] op_sel_hi:[1,0]
	v_pk_mul_f32 v[6:7], v[6:7], v[2:3] op_sel_hi:[1,0]
	v_pk_mul_f32 v[4:5], v[4:5], v[2:3] op_sel_hi:[1,0]
	s_andn2_b64 vcc, exec, s[14:15]
	s_mov_b64 s[14:15], 0
	s_waitcnt vmcnt(0)
	v_pk_mul_f32 v[32:33], v[32:33], v[100:101]
	s_nop 0
	v_pk_mul_f32 v[32:33], v[98:99], v[32:33]
	v_pk_mul_f32 v[98:99], v[104:105], v[2:3] op_sel_hi:[1,0]
	v_cvt_pk_bf16_f32 v32, v32, v33
	v_pk_mul_f32 v[34:35], v[34:35], v[98:99]
	s_nop 0
	v_pk_mul_f32 v[34:35], v[86:87], v[34:35]
	s_nop 0
	v_cvt_pk_bf16_f32 v33, v34, v35
	v_lshl_add_u64 v[34:35], v[68:69], 0, v[84:85]
	global_store_dwordx2 v[34:35], v[32:33], off
	global_load_dwordx4 v[84:87], v[64:65], off offset:64
	v_lshlrev_b32_e32 v32, 16, v82
	v_and_b32_e32 v33, 0xffff0000, v82
	v_mul_f32_e32 v32, 0xbfb8aa3b, v32
	v_mul_f32_e32 v33, 0xbfb8aa3b, v33
	v_exp_f32_e32 v32, v32
	v_exp_f32_e32 v33, v33
	v_add_f32_e32 v32, 1.0, v32
	v_add_f32_e32 v33, 1.0, v33
	v_rcp_f32_e32 v32, v32
	v_rcp_f32_e32 v33, v33
	s_waitcnt vmcnt(0)
	v_pk_mul_f32 v[30:31], v[84:85], v[30:31]
	s_nop 0
	v_pk_mul_f32 v[30:31], v[32:33], v[30:31]
	v_lshlrev_b32_e32 v32, 16, v83
	v_and_b32_e32 v33, 0xffff0000, v83
	v_mul_f32_e32 v32, 0xbfb8aa3b, v32
	v_mul_f32_e32 v33, 0xbfb8aa3b, v33
	v_exp_f32_e32 v32, v32
	v_exp_f32_e32 v33, v33
	v_pk_mul_f32 v[28:29], v[86:87], v[28:29]
	v_cvt_pk_bf16_f32 v30, v30, v31
	v_add_f32_e32 v32, 1.0, v32
	v_add_f32_e32 v33, 1.0, v33
	v_rcp_f32_e32 v32, v32
	v_rcp_f32_e32 v33, v33
	s_nop 0
	v_pk_mul_f32 v[28:29], v[32:33], v[28:29]
	s_nop 0
	v_cvt_pk_bf16_f32 v31, v28, v29
	global_store_dwordx2 v[34:35], v[30:31], off offset:32
	global_load_dwordx4 v[28:31], v[64:65], off offset:128
	v_lshlrev_b32_e32 v32, 16, v80
	v_and_b32_e32 v33, 0xffff0000, v80
	v_mul_f32_e32 v32, 0xbfb8aa3b, v32
	v_mul_f32_e32 v33, 0xbfb8aa3b, v33
	v_exp_f32_e32 v32, v32
	v_exp_f32_e32 v33, v33
	v_add_f32_e32 v32, 1.0, v32
	v_add_f32_e32 v33, 1.0, v33
	v_rcp_f32_e32 v32, v32
	v_rcp_f32_e32 v33, v33
	s_waitcnt vmcnt(0)
	v_pk_mul_f32 v[26:27], v[28:29], v[26:27]
	v_lshlrev_b32_e32 v28, 16, v81
	v_and_b32_e32 v29, 0xffff0000, v81
	v_mul_f32_e32 v28, 0xbfb8aa3b, v28
	v_mul_f32_e32 v29, 0xbfb8aa3b, v29
	v_exp_f32_e32 v28, v28
	v_exp_f32_e32 v29, v29
	v_pk_mul_f32 v[24:25], v[30:31], v[24:25]
	v_pk_mul_f32 v[26:27], v[32:33], v[26:27]
	v_add_f32_e32 v28, 1.0, v28
	v_add_f32_e32 v29, 1.0, v29
	v_rcp_f32_e32 v28, v28
	v_rcp_f32_e32 v29, v29
	v_cvt_pk_bf16_f32 v26, v26, v27
	v_pk_mul_f32 v[24:25], v[28:29], v[24:25]
	s_nop 0
	v_cvt_pk_bf16_f32 v27, v24, v25
	global_store_dwordx2 v[34:35], v[26:27], off offset:64
	global_load_dwordx4 v[24:27], v[64:65], off offset:192
	v_lshlrev_b32_e32 v28, 16, v78
	v_and_b32_e32 v29, 0xffff0000, v78
	v_mul_f32_e32 v28, 0xbfb8aa3b, v28
	v_mul_f32_e32 v29, 0xbfb8aa3b, v29
	v_exp_f32_e32 v28, v28
	v_exp_f32_e32 v29, v29
	v_add_f32_e32 v28, 1.0, v28
	v_add_f32_e32 v29, 1.0, v29
	v_rcp_f32_e32 v28, v28
	v_rcp_f32_e32 v29, v29
	s_waitcnt vmcnt(0)
	v_pk_mul_f32 v[22:23], v[24:25], v[22:23]
	v_lshlrev_b32_e32 v24, 16, v79
	v_and_b32_e32 v25, 0xffff0000, v79
	v_mul_f32_e32 v24, 0xbfb8aa3b, v24
	v_mul_f32_e32 v25, 0xbfb8aa3b, v25
	v_exp_f32_e32 v24, v24
	v_exp_f32_e32 v25, v25
	v_pk_mul_f32 v[20:21], v[26:27], v[20:21]
	v_pk_mul_f32 v[22:23], v[28:29], v[22:23]
	v_add_f32_e32 v24, 1.0, v24
	v_add_f32_e32 v25, 1.0, v25
	v_rcp_f32_e32 v24, v24
	v_rcp_f32_e32 v25, v25
	v_cvt_pk_bf16_f32 v22, v22, v23
	v_pk_mul_f32 v[20:21], v[24:25], v[20:21]
	s_nop 0
	v_cvt_pk_bf16_f32 v23, v20, v21
	global_store_dwordx2 v[34:35], v[22:23], off offset:96
	global_load_dwordx4 v[20:23], v[64:65], off offset:256
	v_lshlrev_b32_e32 v24, 16, v76
	v_and_b32_e32 v25, 0xffff0000, v76
	v_mul_f32_e32 v24, 0xbfb8aa3b, v24
	v_mul_f32_e32 v25, 0xbfb8aa3b, v25
	v_exp_f32_e32 v24, v24
	v_exp_f32_e32 v25, v25
	v_add_f32_e32 v24, 1.0, v24
	v_add_f32_e32 v25, 1.0, v25
	v_rcp_f32_e32 v24, v24
	v_rcp_f32_e32 v25, v25
	s_waitcnt vmcnt(0)
	v_pk_mul_f32 v[18:19], v[20:21], v[18:19]
	v_lshlrev_b32_e32 v20, 16, v77
	v_and_b32_e32 v21, 0xffff0000, v77
	v_mul_f32_e32 v20, 0xbfb8aa3b, v20
	v_mul_f32_e32 v21, 0xbfb8aa3b, v21
	v_exp_f32_e32 v20, v20
	v_exp_f32_e32 v21, v21
	v_pk_mul_f32 v[16:17], v[22:23], v[16:17]
	v_pk_mul_f32 v[18:19], v[24:25], v[18:19]
	v_add_f32_e32 v20, 1.0, v20
	v_add_f32_e32 v21, 1.0, v21
	v_rcp_f32_e32 v20, v20
	v_rcp_f32_e32 v21, v21
	v_cvt_pk_bf16_f32 v18, v18, v19
	v_pk_mul_f32 v[16:17], v[20:21], v[16:17]
	s_nop 0
	v_cvt_pk_bf16_f32 v19, v16, v17
	global_store_dwordx2 v[34:35], v[18:19], off offset:128
	global_load_dwordx4 v[16:19], v[64:65], off offset:320
	v_lshlrev_b32_e32 v20, 16, v74
	v_and_b32_e32 v21, 0xffff0000, v74
	v_mul_f32_e32 v20, 0xbfb8aa3b, v20
	v_mul_f32_e32 v21, 0xbfb8aa3b, v21
	v_exp_f32_e32 v20, v20
	v_exp_f32_e32 v21, v21
	v_add_f32_e32 v20, 1.0, v20
	v_add_f32_e32 v21, 1.0, v21
	v_rcp_f32_e32 v20, v20
	v_rcp_f32_e32 v21, v21
	s_waitcnt vmcnt(0)
	v_pk_mul_f32 v[14:15], v[16:17], v[14:15]
	v_lshlrev_b32_e32 v16, 16, v75
	v_and_b32_e32 v17, 0xffff0000, v75
	v_mul_f32_e32 v16, 0xbfb8aa3b, v16
	v_mul_f32_e32 v17, 0xbfb8aa3b, v17
	v_exp_f32_e32 v16, v16
	v_exp_f32_e32 v17, v17
	v_pk_mul_f32 v[12:13], v[18:19], v[12:13]
	v_pk_mul_f32 v[14:15], v[20:21], v[14:15]
	v_add_f32_e32 v16, 1.0, v16
	v_add_f32_e32 v17, 1.0, v17
	v_rcp_f32_e32 v16, v16
	v_rcp_f32_e32 v17, v17
	v_cvt_pk_bf16_f32 v14, v14, v15
	v_pk_mul_f32 v[12:13], v[16:17], v[12:13]
	s_nop 0
	v_cvt_pk_bf16_f32 v15, v12, v13
	global_store_dwordx2 v[34:35], v[14:15], off offset:160
	global_load_dwordx4 v[12:15], v[64:65], off offset:384
	v_lshlrev_b32_e32 v16, 16, v72
	v_and_b32_e32 v17, 0xffff0000, v72
	v_mul_f32_e32 v16, 0xbfb8aa3b, v16
	v_mul_f32_e32 v17, 0xbfb8aa3b, v17
	v_exp_f32_e32 v16, v16
	v_exp_f32_e32 v17, v17
	v_add_f32_e32 v16, 1.0, v16
	v_add_f32_e32 v17, 1.0, v17
	v_rcp_f32_e32 v16, v16
	v_rcp_f32_e32 v17, v17
	s_waitcnt vmcnt(0)
	v_pk_mul_f32 v[10:11], v[12:13], v[10:11]
	v_lshlrev_b32_e32 v12, 16, v73
	v_and_b32_e32 v13, 0xffff0000, v73
	v_mul_f32_e32 v12, 0xbfb8aa3b, v12
	v_mul_f32_e32 v13, 0xbfb8aa3b, v13
	v_exp_f32_e32 v12, v12
	v_exp_f32_e32 v13, v13
	v_pk_mul_f32 v[8:9], v[14:15], v[8:9]
	v_pk_mul_f32 v[10:11], v[16:17], v[10:11]
	v_add_f32_e32 v12, 1.0, v12
	v_add_f32_e32 v13, 1.0, v13
	v_rcp_f32_e32 v12, v12
	v_rcp_f32_e32 v13, v13
	v_cvt_pk_bf16_f32 v10, v10, v11
	v_pk_mul_f32 v[8:9], v[12:13], v[8:9]
	s_nop 0
	v_cvt_pk_bf16_f32 v11, v8, v9
	global_store_dwordx2 v[34:35], v[10:11], off offset:192
	global_load_dwordx4 v[8:11], v[64:65], off offset:448
	v_lshlrev_b32_e32 v12, 16, v70
	v_and_b32_e32 v13, 0xffff0000, v70
	v_mul_f32_e32 v12, 0xbfb8aa3b, v12
	v_mul_f32_e32 v13, 0xbfb8aa3b, v13
	v_exp_f32_e32 v12, v12
	v_exp_f32_e32 v13, v13
	v_add_f32_e32 v12, 1.0, v12
	v_add_f32_e32 v13, 1.0, v13
	v_rcp_f32_e32 v12, v12
	v_rcp_f32_e32 v13, v13
	s_waitcnt vmcnt(0)
	v_pk_mul_f32 v[6:7], v[8:9], v[6:7]
	v_lshlrev_b32_e32 v8, 16, v71
	v_and_b32_e32 v9, 0xffff0000, v71
	v_mul_f32_e32 v8, 0xbfb8aa3b, v8
	v_mul_f32_e32 v9, 0xbfb8aa3b, v9
	v_exp_f32_e32 v8, v8
	v_exp_f32_e32 v9, v9
	v_pk_mul_f32 v[4:5], v[10:11], v[4:5]
	v_pk_mul_f32 v[6:7], v[12:13], v[6:7]
	v_add_f32_e32 v8, 1.0, v8
	v_add_f32_e32 v9, 1.0, v9
	v_rcp_f32_e32 v8, v8
	v_rcp_f32_e32 v9, v9
	v_cvt_pk_bf16_f32 v6, v6, v7
	v_pk_mul_f32 v[4:5], v[8:9], v[4:5]
	s_nop 0
	v_cvt_pk_bf16_f32 v7, v4, v5
	global_store_dwordx2 v[34:35], v[6:7], off offset:224
	s_cbranch_vccz .LBB0_76
	v_readlane_b32 s14, v252, 7
	v_readlane_b32 s15, v252, 8
	s_load_dword s13, s[14:15], 0x0
	s_waitcnt lgkmcnt(0)
	s_add_i32 s12, s12, s13
	s_cmpk_gt_i32 s12, 0xff
	s_cbranch_scc0 .LBB0_73

.LBB0_217:
	s_lshl_b32 s5, s4, 8
	s_and_b32 s10, s5, 0x1f00
	s_ashr_i32 s5, s4, 31
	s_lshl_b64 s[8:9], s[4:5], 16
	s_waitcnt vmcnt(13)
	v_lshl_add_u64 v[12:13], v[36:37], 0, s[8:9]
	v_lshl_add_u64 v[8:9], v[44:45], 2, v[12:13]
	v_lshl_add_u64 v[68:69], v[46:47], 2, v[12:13]
	v_lshl_add_u64 v[70:71], v[48:49], 2, v[12:13]
	v_lshl_add_u64 v[72:73], v[50:51], 2, v[12:13]
	global_load_dwordx4 v[4:7], v[8:9], off offset:16
	global_load_dwordx4 v[14:17], v[8:9], off
	global_load_dwordx4 v[18:21], v[68:69], off offset:16
	global_load_dwordx4 v[22:25], v[68:69], off
	global_load_dwordx4 v[26:29], v[70:71], off offset:16
	global_load_dwordx4 v[30:33], v[70:71], off
	global_load_dwordx4 v[74:77], v[72:73], off offset:16
	global_load_dwordx4 v[78:81], v[72:73], off
	s_barrier
	s_ashr_i32 s6, s4, 7
	s_ashr_i32 s7, s6, 31
	s_lshl_b64 s[6:7], s[6:7], 13
	s_lshl_b32 s5, s4, 2
	s_or_b32 s6, s6, s10
	s_and_b32 s5, s5, 0x180
	v_lshl_add_u64 v[54:55], s[6:7], 0, v[0:1]
	v_lshl_add_u64 v[58:59], v[40:41], 0, s[6:7]
	s_lshl_b32 s6, s5, 2
	s_mov_b32 s7, s21
	v_lshl_add_u64 v[60:61], v[42:43], 0, s[6:7]
	v_readlane_b32 s6, v254, 50
	s_lshl_b32 s20, s5, 1
	v_readlane_b32 s7, v254, 51
	v_lshl_add_u64 v[56:57], v[38:39], 0, s[20:21]
	v_lshl_add_u64 v[64:65], v[52:53], 0, s[20:21]
	s_mov_b64 s[8:9], 0
	s_movk_i32 s12, 0x1c00
	s_waitcnt vmcnt(6)
	v_cvt_pk_bf16_f32 v8, v14, v15
	v_cvt_pk_bf16_f32 v9, v16, v17
	v_cvt_pk_bf16_f32 v10, v4, v5
	v_cvt_pk_bf16_f32 v11, v6, v7
	ds_write_b128 v93, v[8:11]
	s_waitcnt vmcnt(4)
	v_cvt_pk_bf16_f32 v82, v22, v23
	v_cvt_pk_bf16_f32 v83, v24, v25
	v_cvt_pk_bf16_f32 v84, v18, v19
	v_cvt_pk_bf16_f32 v85, v20, v21
	ds_write_b128 v93, v[82:85] offset:8704
	s_waitcnt vmcnt(2)
	v_cvt_pk_bf16_f32 v14, v30, v31
	v_cvt_pk_bf16_f32 v15, v32, v33
	v_cvt_pk_bf16_f32 v16, v26, v27
	v_cvt_pk_bf16_f32 v17, v28, v29
	ds_write_b128 v93, v[14:17] offset:17408
	s_waitcnt vmcnt(0)
	v_cvt_pk_bf16_f32 v18, v78, v79
	v_cvt_pk_bf16_f32 v19, v80, v81
	v_cvt_pk_bf16_f32 v20, v74, v75
	v_cvt_pk_bf16_f32 v21, v76, v77
	ds_write_b128 v93, v[18:21] offset:26112
	v_or_b32_e32 v4, s5, v88
	v_lshlrev_b32_e32 v2, 2, v4
	v_lshl_add_u64 v[62:63], s[0:1], 0, v[2:3]
	v_lshlrev_b32_e32 v2, 1, v4
	v_lshl_add_u64 v[66:67], s[6:7], 0, v[2:3]
	s_mov_b64 s[6:7], -1
.LBB0_218:
	v_lshl_add_u64 v[4:5], v[54:55], 0, s[8:9]
	v_mad_u64_u32 v[8:9], s[10:11], v4, s12, v[56:57]
	v_mov_b32_e32 v2, v9
	v_mad_u64_u32 v[10:11], s[10:11], v5, s12, v[2:3]
	v_mov_b32_e32 v9, v10
	s_mov_b32 s5, 0x38000
	v_add_co_u32_e32 v114, vcc, s5, v8
	s_mov_b32 s5, 0x70000
	s_nop 0
	v_addc_co_u32_e32 v115, vcc, 0, v10, vcc
	v_add_co_u32_e32 v116, vcc, s5, v8
	s_mov_b32 s5, 0xa8000
	s_nop 0
	v_addc_co_u32_e32 v117, vcc, 0, v10, vcc
	v_add_co_u32_e32 v118, vcc, s5, v8
	s_nop 1
	v_addc_co_u32_e32 v119, vcc, 0, v10, vcc
	global_load_dwordx4 v[120:123], v[8:9], off
	global_load_dwordx4 v[124:127], v[114:115], off
	global_load_dwordx4 v[128:131], v[116:117], off
	global_load_dwordx4 v[132:135], v[118:119], off
	v_lshl_add_u64 v[4:5], v[58:59], 0, s[8:9]
	v_mad_u64_u32 v[68:69], s[8:9], v4, s12, v[64:65]
	v_mov_b32_e32 v2, v69
	v_lshlrev_b64 v[84:85], 11, v[4:5]
	v_mad_u64_u32 v[4:5], s[8:9], v5, s12, v[2:3]
	v_lshl_add_u64 v[32:33], v[60:61], 0, v[84:85]
	v_mov_b32_e32 v69, v4
	global_load_dwordx4 v[24:27], v[32:33], off
	global_load_dwordx2 v[86:87], v[68:69], off offset:3072
	global_load_dwordx4 v[28:31], v[32:33], off offset:64
	global_load_dwordx2 v[80:81], v[68:69], off offset:3104
	global_load_dwordx4 v[20:23], v[32:33], off offset:128
	global_load_dwordx2 v[78:79], v[68:69], off offset:3136
	global_load_dwordx4 v[12:15], v[32:33], off offset:192
	global_load_dwordx2 v[76:77], v[68:69], off offset:3168
	global_load_dwordx4 v[16:19], v[32:33], off offset:256
	global_load_dwordx2 v[74:75], v[68:69], off offset:3200
	global_load_dwordx4 v[8:11], v[32:33], off offset:320
	global_load_dwordx2 v[72:73], v[68:69], off offset:3232
	global_load_dwordx4 v[4:7], v[32:33], off offset:384
	global_load_dwordx2 v[70:71], v[68:69], off offset:3264
	s_nop 0
	global_load_dwordx4 v[32:35], v[32:33], off offset:448
	s_nop 0
	global_load_dwordx2 v[68:69], v[68:69], off offset:3296
	s_waitcnt lgkmcnt(0)
	s_barrier
	s_waitcnt vmcnt(19)
	ds_write_b128 v93, v[120:123] offset:34816
	s_waitcnt vmcnt(18)
	ds_write_b128 v93, v[124:127] offset:43520
	s_waitcnt vmcnt(17)
	ds_write_b128 v93, v[128:131] offset:52224
	s_waitcnt vmcnt(16)
	ds_write_b128 v93, v[132:135] offset:60928
	s_waitcnt lgkmcnt(0)
	s_barrier
	ds_read_b128 v[94:97], v91 offset:34816
	ds_read_b128 v[98:101], v91 offset:34880
	ds_read_b128 v[102:105], v91 offset:34944
	ds_read_b128 v[106:109], v91 offset:35008
	ds_read_b128 v[110:113], v92
	ds_read_b128 v[114:117], v92 offset:64
	ds_read_b128 v[118:121], v92 offset:4416
	s_waitcnt lgkmcnt(2)
	v_mfma_f32_16x16x32_bf16 v[110:113], v[110:113], v[94:97], 0
	ds_read_b128 v[122:125], v92 offset:8768
	ds_read_b128 v[126:129], v92 offset:13120
	ds_read_b128 v[130:133], v92 offset:17472
	s_waitcnt lgkmcnt(4)
	v_mfma_f32_16x16x32_bf16 v[110:113], v[114:117], v[98:101], v[110:113]
	ds_read_b128 v[114:117], v92 offset:128
	s_mov_b64 s[8:9], 0x80
	ds_read_b128 v[134:137], v92 offset:21824
	s_waitcnt lgkmcnt(1)
	v_mfma_f32_16x16x32_bf16 v[110:113], v[114:117], v[102:105], v[110:113]
	ds_read_b128 v[114:117], v92 offset:192
	ds_read_b128 v[138:141], v92 offset:26176
	s_waitcnt lgkmcnt(1)
	v_mfma_f32_16x16x32_bf16 v[110:113], v[114:117], v[106:109], v[110:113]
	ds_read_b128 v[114:117], v92 offset:4352
	s_waitcnt vmcnt(15)
	s_nop 5
	v_pk_add_f32 v[24:25], v[24:25], v[110:111]
	s_waitcnt lgkmcnt(0)
	v_mfma_f32_16x16x32_bf16 v[114:117], v[114:117], v[94:97], 0
	v_mfma_f32_16x16x32_bf16 v[114:117], v[118:121], v[98:101], v[114:117]
	ds_read_b128 v[118:121], v92 offset:4480
	s_waitcnt lgkmcnt(0)
	v_mfma_f32_16x16x32_bf16 v[114:117], v[118:121], v[102:105], v[114:117]
	ds_read_b128 v[118:121], v92 offset:4544
	s_waitcnt lgkmcnt(0)
	v_mfma_f32_16x16x32_bf16 v[114:117], v[118:121], v[106:109], v[114:117]
	ds_read_b128 v[118:121], v92 offset:8704
	s_waitcnt vmcnt(13)
	s_nop 5
	v_pk_add_f32 v[82:83], v[28:29], v[114:115]
	s_waitcnt lgkmcnt(0)
	v_mfma_f32_16x16x32_bf16 v[118:121], v[118:121], v[94:97], 0
	v_add_f32_e64 v30, v30, v116
	v_add_f32_e64 v31, v31, v117
	v_mov_b32_e32 v28, v25
	v_mov_b32_e32 v29, v83
	v_mfma_f32_16x16x32_bf16 v[118:121], v[122:125], v[98:101], v[118:121]
	ds_read_b128 v[122:125], v92 offset:8832
	v_pk_mul_f32 v[28:29], v[28:29], v[28:29]
	s_waitcnt lgkmcnt(0)
	v_mfma_f32_16x16x32_bf16 v[118:121], v[122:125], v[102:105], v[118:121]
	ds_read_b128 v[122:125], v92 offset:8896
	s_waitcnt lgkmcnt(0)
	v_mfma_f32_16x16x32_bf16 v[118:121], v[122:125], v[106:109], v[118:121]
	ds_read_b128 v[122:125], v92 offset:13056
	s_waitcnt lgkmcnt(0)
	v_mfma_f32_16x16x32_bf16 v[122:125], v[122:125], v[94:97], 0
	v_mfma_f32_16x16x32_bf16 v[122:125], v[126:129], v[98:101], v[122:125]
	ds_read_b128 v[126:129], v92 offset:13184
	s_waitcnt lgkmcnt(0)
	v_mfma_f32_16x16x32_bf16 v[122:125], v[126:129], v[102:105], v[122:125]
	ds_read_b128 v[126:129], v92 offset:13248
	s_waitcnt lgkmcnt(0)
	v_mfma_f32_16x16x32_bf16 v[122:125], v[126:129], v[106:109], v[122:125]
	ds_read_b128 v[126:129], v92 offset:17408
	s_waitcnt lgkmcnt(0)
	v_mfma_f32_16x16x32_bf16 v[126:129], v[126:129], v[94:97], 0
	v_mfma_f32_16x16x32_bf16 v[126:129], v[130:133], v[98:101], v[126:129]
	ds_read_b128 v[130:133], v92 offset:17536
	s_waitcnt lgkmcnt(0)
	v_mfma_f32_16x16x32_bf16 v[126:129], v[130:133], v[102:105], v[126:129]
	ds_read_b128 v[130:133], v92 offset:17600
	s_waitcnt lgkmcnt(0)
	v_mfma_f32_16x16x32_bf16 v[126:129], v[130:133], v[106:109], v[126:129]
	ds_read_b128 v[130:133], v92 offset:21760
	s_waitcnt vmcnt(7)
	s_nop 5
	v_pk_add_f32 v[16:17], v[16:17], v[126:127]
	s_waitcnt lgkmcnt(0)
	v_mfma_f32_16x16x32_bf16 v[130:133], v[130:133], v[94:97], 0
	v_mul_f32_e32 v2, v16, v16
	v_pk_add_f32 v[18:19], v[18:19], v[128:129]
	v_mfma_f32_16x16x32_bf16 v[130:133], v[134:137], v[98:101], v[130:133]
	ds_read_b128 v[134:137], v92 offset:21888
	s_waitcnt lgkmcnt(0)
	v_mfma_f32_16x16x32_bf16 v[130:133], v[134:137], v[102:105], v[130:133]
	ds_read_b128 v[134:137], v92 offset:21952
	s_waitcnt lgkmcnt(0)
	v_mfma_f32_16x16x32_bf16 v[130:133], v[134:137], v[106:109], v[130:133]
	ds_read_b128 v[134:137], v92 offset:26112
	s_waitcnt lgkmcnt(0)
	v_mfma_f32_16x16x32_bf16 v[134:137], v[134:137], v[94:97], 0
	v_mfma_f32_16x16x32_bf16 v[134:137], v[138:141], v[98:101], v[134:137]
	ds_read_b128 v[138:141], v92 offset:26240
	s_waitcnt lgkmcnt(0)
	v_mfma_f32_16x16x32_bf16 v[134:137], v[138:141], v[102:105], v[134:137]
	ds_read_b128 v[138:141], v92 offset:26304
	s_waitcnt lgkmcnt(0)
	v_mfma_f32_16x16x32_bf16 v[134:137], v[138:141], v[106:109], v[134:137]
	ds_read_b128 v[138:141], v92 offset:30464
	s_waitcnt lgkmcnt(0)
	v_mfma_f32_16x16x32_bf16 v[94:97], v[138:141], v[94:97], 0
	ds_read_b128 v[138:141], v92 offset:30528
	s_waitcnt lgkmcnt(0)
	v_mfma_f32_16x16x32_bf16 v[94:97], v[138:141], v[98:101], v[94:97]
	ds_read_b128 v[98:101], v92 offset:30592
	s_waitcnt lgkmcnt(0)
	v_mfma_f32_16x16x32_bf16 v[94:97], v[98:101], v[102:105], v[94:97]
	ds_read_b128 v[98:101], v92 offset:30656
	v_mul_f32_e32 v104, v17, v17
	v_mul_f32_e32 v105, v18, v18
	s_waitcnt lgkmcnt(0)
	v_mfma_f32_16x16x32_bf16 v[94:97], v[98:101], v[106:109], v[94:97]
	v_add_f32_e64 v98, v26, v112
	v_add_f32_e64 v99, v27, v113
	v_mov_b32_e32 v26, v24
	v_mov_b32_e32 v27, v82
	v_mov_b32_e32 v100, v99
	v_mov_b32_e32 v101, v31
	v_pk_fma_f32 v[26:27], v[26:27], v[26:27], v[28:29]
	v_mov_b32_e32 v28, v98
	v_mov_b32_e32 v29, v30
	v_pk_mul_f32 v[100:101], v[100:101], v[100:101]
	v_mul_f32_e32 v106, v19, v19
	v_pk_fma_f32 v[28:29], v[28:29], v[28:29], v[100:101]
	s_nop 0
	v_pk_add_f32 v[100:101], v[26:27], v[28:29]
	v_pk_add_f32 v[26:27], v[22:23], v[120:121]
	v_pk_add_f32 v[28:29], v[20:21], v[118:119]
	v_pk_mul_f32 v[20:21], v[26:27], v[26:27]
	v_pk_mul_f32 v[22:23], v[28:29], v[28:29]
	s_nop 0
	v_pk_mov_b32 v[102:103], v[22:23], v[20:21] op_sel:[1,0]
	v_mov_b32_e32 v23, v21
	v_pk_add_f32 v[102:103], v[102:103], v[22:23]
	v_pk_add_f32 v[20:21], v[14:15], v[124:125]
	v_pk_add_f32 v[22:23], v[12:13], v[122:123]
	v_pk_add_f32 v[12:13], v[100:101], v[100:101] op_sel:[0,1] op_sel_hi:[1,0]
	v_pk_add_f32 v[14:15], v[102:103], v[102:103] op_sel:[0,1] op_sel_hi:[1,0]
	v_mov_b32_e32 v13, v2
	v_mov_b32_e32 v15, v104
	v_mul_f32_e32 v2, v23, v23
	v_pk_add_f32 v[12:13], v[12:13], v[14:15]
	v_pk_fma_f32 v[14:15], v[22:23], v[22:23], v[2:3] op_sel_hi:[1,1,0]
	v_mul_f32_e32 v2, v21, v21
	v_pk_fma_f32 v[100:101], v[20:21], v[20:21], v[2:3] op_sel_hi:[1,1,0]
	v_mov_b32_e32 v15, v105
	v_mov_b32_e32 v101, v106
	v_pk_add_f32 v[14:15], v[14:15], v[100:101]
	s_nop 0
	v_pk_add_f32 v[100:101], v[12:13], v[14:15]
	s_waitcnt vmcnt(5)
	v_pk_add_f32 v[12:13], v[10:11], v[132:133]
	v_pk_add_f32 v[14:15], v[8:9], v[130:131]
	v_pk_mul_f32 v[8:9], v[12:13], v[12:13]
	v_pk_mul_f32 v[10:11], v[14:15], v[14:15]
	s_nop 0
	v_pk_mov_b32 v[102:103], v[10:11], v[8:9] op_sel:[1,0]
	v_mov_b32_e32 v11, v9
	v_pk_add_f32 v[102:103], v[102:103], v[10:11]
	s_waitcnt vmcnt(3)
	v_pk_add_f32 v[8:9], v[6:7], v[136:137]
	s_waitcnt vmcnt(1)
	v_pk_add_f32 v[6:7], v[32:33], v[94:95]
	v_pk_add_f32 v[10:11], v[4:5], v[134:135]
	v_pk_add_f32 v[4:5], v[34:35], v[96:97]
	v_mul_f32_e32 v2, v6, v6
	v_mul_f32_e32 v94, v7, v7
	v_pk_add_f32 v[32:33], v[100:101], v[100:101] op_sel:[0,1] op_sel_hi:[1,0]
	v_pk_add_f32 v[34:35], v[102:103], v[102:103] op_sel:[0,1] op_sel_hi:[1,0]
	v_mov_b32_e32 v33, v2
	v_mov_b32_e32 v35, v94
	v_mul_f32_e32 v2, v11, v11
	v_mul_f32_e32 v95, v4, v4
	v_pk_add_f32 v[32:33], v[32:33], v[34:35]
	v_pk_fma_f32 v[34:35], v[10:11], v[10:11], v[2:3] op_sel_hi:[1,1,0]
	v_mul_f32_e32 v2, v9, v9
	v_mul_f32_e32 v96, v5, v5
	v_mov_b32_e32 v35, v95
	v_pk_fma_f32 v[94:95], v[8:9], v[8:9], v[2:3] op_sel_hi:[1,1,0]
	s_nop 0
	v_mov_b32_e32 v95, v96
	v_pk_add_f32 v[34:35], v[34:35], v[94:95]
	v_lshlrev_b32_e32 v94, 16, v86
	v_pk_add_f32 v[32:33], v[32:33], v[34:35]
	v_and_b32_e32 v95, 0xffff0000, v86
	v_add_f32_e32 v2, v32, v33
	ds_bpermute_b32 v32, v89, v2
	v_mul_f32_e32 v86, 0xbfb8aa3b, v94
	v_exp_f32_e32 v86, v86
	s_waitcnt lgkmcnt(0)
	v_add_f32_e32 v2, v2, v32
	ds_bpermute_b32 v32, v90, v2
	v_add_f32_e32 v86, 1.0, v86
	v_rcp_f32_e32 v96, v86
	s_waitcnt lgkmcnt(0)
	v_add_f32_e32 v2, v2, v32
	v_fmamk_f32 v2, v2, 0x3c000000, v172
	v_cmp_gt_f32_e32 vcc, s33, v2
	v_mul_f32_e32 v32, 0x4b800000, v2
	s_nop 0
	v_cndmask_b32_e32 v2, v2, v32, vcc
	v_rsq_f32_e32 v2, v2
	s_nop 0
	v_mul_f32_e32 v32, 0x45800000, v2
	v_cndmask_b32_e32 v2, v2, v32, vcc
	global_load_dwordx4 v[32:35], v[62:63], off
	v_pk_mul_f32 v[24:25], v[24:25], v[2:3] op_sel_hi:[1,0]
	v_pk_mul_f32 v[82:83], v[82:83], v[2:3] op_sel_hi:[1,0]
	v_pk_mul_f32 v[30:31], v[30:31], v[2:3] op_sel_hi:[1,0]
	v_pk_mul_f32 v[28:29], v[28:29], v[2:3] op_sel_hi:[1,0]
	v_pk_mul_f32 v[26:27], v[26:27], v[2:3] op_sel_hi:[1,0]
	v_pk_mul_f32 v[22:23], v[22:23], v[2:3] op_sel_hi:[1,0]
	v_pk_mul_f32 v[20:21], v[20:21], v[2:3] op_sel_hi:[1,0]
	v_pk_mul_f32 v[16:17], v[16:17], v[2:3] op_sel_hi:[1,0]
	v_pk_mul_f32 v[18:19], v[18:19], v[2:3] op_sel_hi:[1,0]
	v_pk_mul_f32 v[14:15], v[14:15], v[2:3] op_sel_hi:[1,0]
	v_pk_mul_f32 v[12:13], v[12:13], v[2:3] op_sel_hi:[1,0]
	v_pk_mul_f32 v[10:11], v[10:11], v[2:3] op_sel_hi:[1,0]
	v_pk_mul_f32 v[8:9], v[8:9], v[2:3] op_sel_hi:[1,0]
	v_pk_mul_f32 v[6:7], v[6:7], v[2:3] op_sel_hi:[1,0]
	v_pk_mul_f32 v[4:5], v[4:5], v[2:3] op_sel_hi:[1,0]
	s_andn2_b64 vcc, exec, s[6:7]
	s_mov_b64 s[6:7], 0
	s_waitcnt vmcnt(0)
	v_pk_mul_f32 v[24:25], v[32:33], v[24:25]
	v_mul_f32_e32 v32, 0xbfb8aa3b, v95
	v_exp_f32_e32 v32, v32
	s_nop 0
	v_add_f32_e32 v32, 1.0, v32
	v_rcp_f32_e32 v97, v32
	s_nop 0
	v_pk_mul_f32 v[32:33], v[96:97], v[94:95]
	s_nop 0
	v_pk_mul_f32 v[24:25], v[32:33], v[24:25]
	v_lshlrev_b32_e32 v32, 16, v87
	v_and_b32_e32 v33, 0xffff0000, v87
	v_mul_f32_e32 v86, 0xbfb8aa3b, v32
	v_mul_f32_e32 v87, 0xbfb8aa3b, v33
	v_exp_f32_e32 v86, v86
	v_exp_f32_e32 v87, v87
	v_pk_mul_f32 v[94:95], v[98:99], v[2:3] op_sel_hi:[1,0]
	v_add_f32_e32 v86, 1.0, v86
	v_add_f32_e32 v87, 1.0, v87
	v_rcp_f32_e32 v86, v86
	v_rcp_f32_e32 v87, v87
	v_pk_mul_f32 v[34:35], v[34:35], v[94:95]
	v_pk_mul_f32 v[32:33], v[86:87], v[32:33]
	s_nop 0
	v_pk_mul_f32 v[34:35], v[32:33], v[34:35]
	v_cvt_pk_bf16_f32 v32, v24, v25
	v_cvt_pk_bf16_f32 v33, v34, v35
	v_lshl_add_u64 v[24:25], v[66:67], 0, v[84:85]
	global_store_dwordx2 v[24:25], v[32:33], off
	global_load_dwordx4 v[32:35], v[62:63], off offset:64
	v_lshlrev_b32_e32 v84, 16, v80
	v_and_b32_e32 v85, 0xffff0000, v80
	v_mul_f32_e32 v80, 0xbfb8aa3b, v84
	v_exp_f32_e32 v80, v80
	s_waitcnt vmcnt(0)
	v_pk_mul_f32 v[32:33], v[32:33], v[82:83]
	v_add_f32_e32 v80, 1.0, v80
	v_rcp_f32_e32 v86, v80
	v_mul_f32_e32 v80, 0xbfb8aa3b, v85
	v_exp_f32_e32 v80, v80
	v_pk_mul_f32 v[30:31], v[34:35], v[30:31]
	v_add_f32_e32 v80, 1.0, v80
	v_rcp_f32_e32 v87, v80
	v_lshlrev_b32_e32 v80, 16, v81
	v_and_b32_e32 v81, 0xffff0000, v81
	v_mul_f32_e32 v34, 0xbfb8aa3b, v81
	v_pk_mul_f32 v[82:83], v[86:87], v[84:85]
	v_exp_f32_e32 v34, v34
	v_pk_mul_f32 v[32:33], v[82:83], v[32:33]
	v_mul_f32_e32 v82, 0xbfb8aa3b, v80
	v_exp_f32_e32 v82, v82
	v_add_f32_e32 v34, 1.0, v34
	v_rcp_f32_e32 v83, v34
	v_cvt_pk_bf16_f32 v32, v32, v33
	v_add_f32_e32 v82, 1.0, v82
	v_rcp_f32_e32 v82, v82
	s_nop 0
	v_pk_mul_f32 v[34:35], v[82:83], v[80:81]
	s_nop 0
	v_pk_mul_f32 v[30:31], v[34:35], v[30:31]
	v_lshlrev_b32_e32 v34, 16, v78
	v_cvt_pk_bf16_f32 v33, v30, v31
	global_store_dwordx2 v[24:25], v[32:33], off offset:32
	global_load_dwordx4 v[30:33], v[62:63], off offset:128
	v_and_b32_e32 v35, 0xffff0000, v78
	v_mul_f32_e32 v78, 0xbfb8aa3b, v34
	v_exp_f32_e32 v78, v78
	s_waitcnt vmcnt(0)
	v_pk_mul_f32 v[28:29], v[30:31], v[28:29]
	v_mul_f32_e32 v30, 0xbfb8aa3b, v35
	v_exp_f32_e32 v30, v30
	v_add_f32_e32 v78, 1.0, v78
	v_rcp_f32_e32 v80, v78
	v_pk_mul_f32 v[26:27], v[32:33], v[26:27]
	v_add_f32_e32 v30, 1.0, v30
	v_rcp_f32_e32 v81, v30
	s_nop 0
	v_pk_mul_f32 v[30:31], v[80:81], v[34:35]
	s_nop 0
	v_pk_mul_f32 v[28:29], v[30:31], v[28:29]
	v_lshlrev_b32_e32 v30, 16, v79
	v_and_b32_e32 v31, 0xffff0000, v79
	v_mul_f32_e32 v34, 0xbfb8aa3b, v30
	v_mul_f32_e32 v32, 0xbfb8aa3b, v31
	v_exp_f32_e32 v34, v34
	v_exp_f32_e32 v32, v32
	v_cvt_pk_bf16_f32 v28, v28, v29
	v_add_f32_e32 v34, 1.0, v34
	v_add_f32_e32 v32, 1.0, v32
	v_rcp_f32_e32 v34, v34
	v_rcp_f32_e32 v35, v32
	s_nop 0
	v_pk_mul_f32 v[30:31], v[34:35], v[30:31]
	s_nop 0
	v_pk_mul_f32 v[26:27], v[30:31], v[26:27]
	v_lshlrev_b32_e32 v30, 16, v76
	v_cvt_pk_bf16_f32 v29, v26, v27
	global_store_dwordx2 v[24:25], v[28:29], off offset:64
	global_load_dwordx4 v[26:29], v[62:63], off offset:192
	v_and_b32_e32 v31, 0xffff0000, v76
	v_mul_f32_e32 v32, 0xbfb8aa3b, v30
	v_exp_f32_e32 v32, v32
	s_waitcnt vmcnt(0)
	v_pk_mul_f32 v[22:23], v[26:27], v[22:23]
	v_mul_f32_e32 v26, 0xbfb8aa3b, v31
	v_exp_f32_e32 v26, v26
	v_add_f32_e32 v32, 1.0, v32
	v_rcp_f32_e32 v32, v32
	v_pk_mul_f32 v[20:21], v[28:29], v[20:21]
	v_add_f32_e32 v26, 1.0, v26
	v_rcp_f32_e32 v33, v26
	s_nop 0
	v_pk_mul_f32 v[26:27], v[32:33], v[30:31]
	s_nop 0
	v_pk_mul_f32 v[22:23], v[26:27], v[22:23]
	v_lshlrev_b32_e32 v26, 16, v77
	v_and_b32_e32 v27, 0xffff0000, v77
	v_mul_f32_e32 v30, 0xbfb8aa3b, v26
	v_mul_f32_e32 v28, 0xbfb8aa3b, v27
	v_exp_f32_e32 v30, v30
	v_exp_f32_e32 v28, v28
	v_cvt_pk_bf16_f32 v22, v22, v23
	v_add_f32_e32 v30, 1.0, v30
	v_add_f32_e32 v28, 1.0, v28
	v_rcp_f32_e32 v30, v30
	v_rcp_f32_e32 v31, v28
	s_nop 0
	v_pk_mul_f32 v[26:27], v[30:31], v[26:27]
	s_nop 0
	v_pk_mul_f32 v[20:21], v[26:27], v[20:21]
	v_lshlrev_b32_e32 v26, 16, v74
	v_cvt_pk_bf16_f32 v23, v20, v21
	global_store_dwordx2 v[24:25], v[22:23], off offset:96
	global_load_dwordx4 v[20:23], v[62:63], off offset:256
	v_and_b32_e32 v27, 0xffff0000, v74
	v_mul_f32_e32 v28, 0xbfb8aa3b, v26
	v_exp_f32_e32 v28, v28
	s_waitcnt vmcnt(0)
	v_pk_mul_f32 v[16:17], v[20:21], v[16:17]
	v_mul_f32_e32 v20, 0xbfb8aa3b, v27
	v_exp_f32_e32 v20, v20
	v_add_f32_e32 v28, 1.0, v28
	v_rcp_f32_e32 v28, v28
	v_pk_mul_f32 v[18:19], v[22:23], v[18:19]
	v_add_f32_e32 v20, 1.0, v20
	v_rcp_f32_e32 v29, v20
	s_nop 0
	v_pk_mul_f32 v[20:21], v[28:29], v[26:27]
	s_nop 0
	v_pk_mul_f32 v[16:17], v[20:21], v[16:17]
	v_lshlrev_b32_e32 v20, 16, v75
	v_and_b32_e32 v21, 0xffff0000, v75
	v_mul_f32_e32 v26, 0xbfb8aa3b, v20
	v_mul_f32_e32 v22, 0xbfb8aa3b, v21
	v_exp_f32_e32 v26, v26
	v_exp_f32_e32 v22, v22
	v_cvt_pk_bf16_f32 v16, v16, v17
	v_add_f32_e32 v26, 1.0, v26
	v_add_f32_e32 v22, 1.0, v22
	v_rcp_f32_e32 v26, v26
	v_rcp_f32_e32 v27, v22
	s_nop 0
	v_pk_mul_f32 v[20:21], v[26:27], v[20:21]
	s_nop 0
	v_pk_mul_f32 v[18:19], v[20:21], v[18:19]
	v_lshlrev_b32_e32 v20, 16, v72
	v_cvt_pk_bf16_f32 v17, v18, v19
	global_store_dwordx2 v[24:25], v[16:17], off offset:128
	global_load_dwordx4 v[16:19], v[62:63], off offset:320
	v_and_b32_e32 v21, 0xffff0000, v72
	v_mul_f32_e32 v22, 0xbfb8aa3b, v20
	v_exp_f32_e32 v22, v22
	s_waitcnt vmcnt(0)
	v_pk_mul_f32 v[14:15], v[16:17], v[14:15]
	v_mul_f32_e32 v16, 0xbfb8aa3b, v21
	v_exp_f32_e32 v16, v16
	v_add_f32_e32 v22, 1.0, v22
	v_rcp_f32_e32 v22, v22
	v_pk_mul_f32 v[12:13], v[18:19], v[12:13]
	v_add_f32_e32 v16, 1.0, v16
	v_rcp_f32_e32 v23, v16
	s_nop 0
	v_pk_mul_f32 v[16:17], v[22:23], v[20:21]
	s_nop 0
	v_pk_mul_f32 v[14:15], v[16:17], v[14:15]
	v_lshlrev_b32_e32 v16, 16, v73
	v_and_b32_e32 v17, 0xffff0000, v73
	v_mul_f32_e32 v20, 0xbfb8aa3b, v16
	v_mul_f32_e32 v18, 0xbfb8aa3b, v17
	v_exp_f32_e32 v20, v20
	v_exp_f32_e32 v18, v18
	v_cvt_pk_bf16_f32 v14, v14, v15
	v_add_f32_e32 v20, 1.0, v20
	v_add_f32_e32 v18, 1.0, v18
	v_rcp_f32_e32 v20, v20
	v_rcp_f32_e32 v21, v18
	s_nop 0
	v_pk_mul_f32 v[16:17], v[20:21], v[16:17]
	s_nop 0
	v_pk_mul_f32 v[12:13], v[16:17], v[12:13]
	v_lshlrev_b32_e32 v16, 16, v70
	v_cvt_pk_bf16_f32 v15, v12, v13
	global_store_dwordx2 v[24:25], v[14:15], off offset:160
	global_load_dwordx4 v[12:15], v[62:63], off offset:384
	v_and_b32_e32 v17, 0xffff0000, v70
	v_mul_f32_e32 v18, 0xbfb8aa3b, v16
	v_exp_f32_e32 v18, v18
	s_waitcnt vmcnt(0)
	v_pk_mul_f32 v[10:11], v[12:13], v[10:11]
	v_mul_f32_e32 v12, 0xbfb8aa3b, v17
	v_exp_f32_e32 v12, v12
	v_add_f32_e32 v18, 1.0, v18
	v_rcp_f32_e32 v18, v18
	v_pk_mul_f32 v[8:9], v[14:15], v[8:9]
	v_add_f32_e32 v12, 1.0, v12
	v_rcp_f32_e32 v19, v12
	s_nop 0
	v_pk_mul_f32 v[12:13], v[18:19], v[16:17]
	s_nop 0
	v_pk_mul_f32 v[10:11], v[12:13], v[10:11]
	v_lshlrev_b32_e32 v12, 16, v71
	v_and_b32_e32 v13, 0xffff0000, v71
	v_mul_f32_e32 v16, 0xbfb8aa3b, v12
	v_mul_f32_e32 v14, 0xbfb8aa3b, v13
	v_exp_f32_e32 v16, v16
	v_exp_f32_e32 v14, v14
	v_cvt_pk_bf16_f32 v10, v10, v11
	v_add_f32_e32 v16, 1.0, v16
	v_add_f32_e32 v14, 1.0, v14
	v_rcp_f32_e32 v16, v16
	v_rcp_f32_e32 v17, v14
	s_nop 0
	v_pk_mul_f32 v[12:13], v[16:17], v[12:13]
	s_nop 0
	v_pk_mul_f32 v[8:9], v[12:13], v[8:9]
	v_lshlrev_b32_e32 v12, 16, v68
	v_cvt_pk_bf16_f32 v11, v8, v9
	global_store_dwordx2 v[24:25], v[10:11], off offset:192
	global_load_dwordx4 v[8:11], v[62:63], off offset:448
	v_and_b32_e32 v13, 0xffff0000, v68
	v_mul_f32_e32 v14, 0xbfb8aa3b, v12
	v_exp_f32_e32 v14, v14
	s_waitcnt vmcnt(0)
	v_pk_mul_f32 v[6:7], v[6:7], v[8:9]
	v_mul_f32_e32 v8, 0xbfb8aa3b, v13
	v_exp_f32_e32 v8, v8
	v_add_f32_e32 v14, 1.0, v14
	v_rcp_f32_e32 v14, v14
	v_pk_mul_f32 v[4:5], v[4:5], v[10:11]
	v_add_f32_e32 v8, 1.0, v8
	v_rcp_f32_e32 v15, v8
	s_nop 0
	v_pk_mul_f32 v[8:9], v[14:15], v[12:13]
	s_nop 0
	v_pk_mul_f32 v[6:7], v[8:9], v[6:7]
	v_lshlrev_b32_e32 v8, 16, v69
	v_and_b32_e32 v9, 0xffff0000, v69
	v_mul_f32_e32 v12, 0xbfb8aa3b, v8
	v_mul_f32_e32 v2, 0xbfb8aa3b, v9
	v_exp_f32_e32 v12, v12
	v_exp_f32_e32 v2, v2
	v_cvt_pk_bf16_f32 v6, v6, v7
	v_add_f32_e32 v12, 1.0, v12
	v_add_f32_e32 v2, 1.0, v2
	v_rcp_f32_e32 v12, v12
	v_rcp_f32_e32 v13, v2
	s_nop 0
	v_pk_mul_f32 v[8:9], v[12:13], v[8:9]
	s_nop 0
	v_pk_mul_f32 v[4:5], v[8:9], v[4:5]
	s_nop 0
	v_cvt_pk_bf16_f32 v7, v4, v5
	global_store_dwordx2 v[24:25], v[6:7], off offset:224
	s_cbranch_vccz .LBB0_218
	v_readlane_b32 s6, v252, 7
	v_readlane_b32 s7, v252, 8
	s_load_dword s5, s[6:7], 0x0
	s_waitcnt lgkmcnt(0)
	s_add_i32 s4, s4, s5
	s_cmpk_gt_i32 s4, 0xff
	s_cbranch_scc0 .LBB0_217
